# all five GEMM loops now issue LDS-DMA with SGPR base + VGPR offset (RET/NAT/SWA projection loops converted too)
# baseline (speedup 1.0000x reference)
; #define PG8_STAGE(bufoff, gbase, voff) do { _Pragma("unroll") for (int _i = 0; _i < 2; ++_i) \
;         __builtin_amdgcn_global_load_lds((const unsigned*)((const char*)(gbase) + (voff)[_i]), (LAS unsigned*)(lds + (bufoff) + ldsw + _i * 8192), 16, 0, 0); } while (0)
; #define PG8_LDA(dst, b, h) do { _Pragma("unroll") for (int m = 0; m < 4; ++m) _Pragma("unroll") for (int k = 0; k < 2; ++k) dst[m][k] = *(const LAS bf16x8*)(lds + PG8_SA(b, h) + aoff + m * 2048 + k * 1024); } while (0)
; #define PG8_LDB(dst, b, h) do { _Pragma("unroll") for (int n = 0; n < 2; ++n) _Pragma("unroll") for (int k = 0; k < 2; ++k) dst[n][k] = *(const LAS bf16x8*)(lds + PG8_SB(b, h) + boff + n * 2048 + k * 1024); } while (0)
; #define PG8_MMA(ai, bj, At, Bt) do { __builtin_amdgcn_s_setprio(1); _Pragma("unroll") for (int m = 0; m < 4; ++m) _Pragma("unroll") for (int n = 0; n < 2; ++n) _Pragma("unroll") for (int k = 0; k < 2; ++k) \
;         acc[ai][bj][m][n] = __builtin_amdgcn_mfma_f32_16x16x32_bf16(Bt[n][k], At[m][k], acc[ai][bj][m][n], 0, 0, 0); __builtin_amdgcn_s_setprio(0); } while (0)
; #define PG8_WAIT_V(n) asm volatile("s_waitcnt vmcnt(" #n ")" ::: "memory")
; #define PG8_WAIT_L(n) asm volatile("s_waitcnt lgkmcnt(" #n ")" ::: "memory")
; #define PG8_BAR __builtin_amdgcn_s_barrier()
; #define PG8_SCHED __builtin_amdgcn_sched_barrier(0)
; template <class Epi>
; DI void gemm_phase(LAS unsigned char* lds, const Gemm g, const StaticOrder S, const Epi E) {
;     ...
;             const bool last = (t == nt - 2);
;             const char* a1 = cA + (size_t)(t + 1) * kstep;
;             const char* a2 = last ? nA : cA + (size_t)(t + 2) * kstep; const char* b2 = last ? nB : cB + (size_t)(t + 2) * kstep;
;             const char* a3 = a2 + kstep; const char* b3 = b2 + kstep;
;             PG8_LDB(B0, 0, 0); PG8_LDB(B1, 0, 1); PG8_SCHED; PG8_LDA(At, 0, 0); PG8_STAGE(PG8_SA(1, 1), a1 + hstepA, voffA);
;             PG8_WAIT_V(8); PG8_WAIT_L(0); PG8_BAR; PG8_MMA(0, 0, At, B0); PG8_MMA(0, 1, At, B1); PG8_BAR; PG8_SCHED;
;             PG8_LDA(At, 0, 1); PG8_STAGE(PG8_SB(0, 0), b2, voffB); PG8_STAGE(PG8_SB(0, 1), b2 + hstepB, voffB); PG8_STAGE(PG8_SA(0, 0), a2, voffA);
.LBB0_241:
	s_add_u32 s20, s44, 0xfffc0080
	s_addc_u32 s21, s45, -1
	s_add_i32 s26, 0, 0x10000
	s_cmp_eq_u32 s79, 12
	s_cselect_b32 s61, s53, s21
	s_cselect_b32 s60, s52, s20
	s_cselect_b32 s31, s55, s51
	s_cselect_b32 s30, s54, s49
	s_add_u32 s98, s30, 0x80
	s_addc_u32 s99, s31, 0
	s_add_u32 s100, s60, 0x80
	s_addc_u32 s101, s61, 0
	s_add_i32 s27, 0, 0x14000
	v_add_u32_e32 v140, s26, v183
	v_add_u32_e32 v144, s27, v183
	ds_read_b128 v[128:131], v140
	ds_read_b128 v[132:135], v140 offset:1024
	ds_read_b128 v[136:139], v140 offset:2048
	ds_read_b128 v[140:143], v140 offset:3072
	ds_read_b128 v[170:173], v144
	ds_read_b128 v[174:177], v144 offset:1024
	ds_read_b128 v[178:181], v144 offset:2048
	ds_read_b128 v[186:189], v144 offset:3072
	s_add_i32 m0, s57, 0xc000
	ds_read_b128 v[190:193], v184
	ds_read_b128 v[194:197], v184 offset:1024
	ds_read_b128 v[220:223], v184 offset:2048
	ds_read_b128 v[230:233], v184 offset:3072
	ds_read_b128 v[234:237], v184 offset:4096
	ds_read_b128 v[238:241], v184 offset:5120
	ds_read_b128 v[242:245], v184 offset:6144
	ds_read_b128 v[246:249], v184 offset:7168
	global_load_lds_dwordx4 v166, s[44:45]
	s_add_i32 m0, s57, 0xe000
	s_nop 0
	global_load_lds_dwordx4 v168, s[44:45]
	s_waitcnt vmcnt(8)
	s_waitcnt lgkmcnt(0)
	s_barrier
	s_setprio 1
	s_waitcnt lgkmcnt(0)
	v_mfma_f32_16x16x32_bf16 v[124:127], v[128:131], v[190:193], v[124:127]
	v_mfma_f32_16x16x32_bf16 v[120:123], v[136:139], v[190:193], v[120:123]
	v_mfma_f32_16x16x32_bf16 v[108:111], v[128:131], v[220:223], v[108:111]
	v_mfma_f32_16x16x32_bf16 v[104:107], v[136:139], v[220:223], v[104:107]
	v_mfma_f32_16x16x32_bf16 v[92:95], v[128:131], v[234:237], v[92:95]
	v_mfma_f32_16x16x32_bf16 v[88:91], v[136:139], v[234:237], v[88:91]
	v_mfma_f32_16x16x32_bf16 v[76:79], v[128:131], v[242:245], v[76:79]
	v_mfma_f32_16x16x32_bf16 v[72:75], v[136:139], v[242:245], v[72:75]
	v_mfma_f32_16x16x32_bf16 v[124:127], v[132:135], v[194:197], v[124:127]
	v_mfma_f32_16x16x32_bf16 v[120:123], v[140:143], v[194:197], v[120:123]
	v_mfma_f32_16x16x32_bf16 v[108:111], v[132:135], v[230:233], v[108:111]
	v_mfma_f32_16x16x32_bf16 v[104:107], v[140:143], v[230:233], v[104:107]
	v_mfma_f32_16x16x32_bf16 v[92:95], v[132:135], v[238:241], v[92:95]
	v_mfma_f32_16x16x32_bf16 v[88:91], v[140:143], v[238:241], v[88:91]
	v_mfma_f32_16x16x32_bf16 v[76:79], v[132:135], v[246:249], v[76:79]
	v_mfma_f32_16x16x32_bf16 v[72:75], v[140:143], v[246:249], v[72:75]
	s_setprio 0
	s_setprio 1
	v_mfma_f32_16x16x32_bf16 v[116:119], v[170:173], v[190:193], v[116:119]
	v_mfma_f32_16x16x32_bf16 v[112:115], v[178:181], v[190:193], v[112:115]
	v_mfma_f32_16x16x32_bf16 v[100:103], v[170:173], v[220:223], v[100:103]
	v_mfma_f32_16x16x32_bf16 v[96:99], v[178:181], v[220:223], v[96:99]
	v_mfma_f32_16x16x32_bf16 v[84:87], v[170:173], v[234:237], v[84:87]
	v_mfma_f32_16x16x32_bf16 v[80:83], v[178:181], v[234:237], v[80:83]
	v_mfma_f32_16x16x32_bf16 v[68:71], v[170:173], v[242:245], v[68:71]
	v_mfma_f32_16x16x32_bf16 v[64:67], v[178:181], v[242:245], v[64:67]
	v_mfma_f32_16x16x32_bf16 v[116:119], v[174:177], v[194:197], v[116:119]
	v_mfma_f32_16x16x32_bf16 v[112:115], v[186:189], v[194:197], v[112:115]
	v_mfma_f32_16x16x32_bf16 v[100:103], v[174:177], v[230:233], v[100:103]
	v_mfma_f32_16x16x32_bf16 v[96:99], v[186:189], v[230:233], v[96:99]
	v_mfma_f32_16x16x32_bf16 v[84:87], v[174:177], v[238:241], v[84:87]
	v_mfma_f32_16x16x32_bf16 v[80:83], v[186:189], v[238:241], v[80:83]
	v_mfma_f32_16x16x32_bf16 v[68:71], v[174:177], v[246:249], v[68:71]
	v_mfma_f32_16x16x32_bf16 v[64:67], v[186:189], v[246:249], v[64:67]
	s_setprio 0
	s_barrier
	s_add_i32 s20, s26, s62
	s_mov_b32 m0, s20
	ds_read_b128 v[190:193], v184 offset:16384
	ds_read_b128 v[194:197], v184 offset:17408
	ds_read_b128 v[220:223], v184 offset:18432
	ds_read_b128 v[230:233], v184 offset:19456
	ds_read_b128 v[234:237], v184 offset:20480
	ds_read_b128 v[238:241], v184 offset:21504
	ds_read_b128 v[242:245], v184 offset:22528
	ds_read_b128 v[246:249], v184 offset:23552
	global_load_lds_dwordx4 v160, s[30:31]
	s_add_i32 m0, s20, 0x2000
	s_add_u32 s20, s30, 0x40000
	s_addc_u32 s21, s31, 0
	s_add_i32 s26, s27, s62
	global_load_lds_dwordx4 v164, s[30:31]
	s_mov_b32 m0, s26
	s_nop 0
	global_load_lds_dwordx4 v160, s[20:21]
	s_add_i32 m0, s26, 0x2000
	s_nop 0
	global_load_lds_dwordx4 v164, s[20:21]
	s_mov_b32 m0, s57
	s_nop 0
	global_load_lds_dwordx4 v158, s[60:61]
	s_mov_b32 m0, s59
	s_nop 0
	global_load_lds_dwordx4 v162, s[60:61]
	s_waitcnt vmcnt(8)
	s_waitcnt lgkmcnt(0)
	s_barrier
; #define PG8_STAGE(bufoff, gbase, voff) do { _Pragma("unroll") for (int _i = 0; _i < 2; ++_i) \
;         __builtin_amdgcn_global_load_lds((const unsigned*)((const char*)(gbase) + (voff)[_i]), (LAS unsigned*)(lds + (bufoff) + ldsw + _i * 8192), 16, 0, 0); } while (0)
; #define PG8_LDA(dst, b, h) do { _Pragma("unroll") for (int m = 0; m < 4; ++m) _Pragma("unroll") for (int k = 0; k < 2; ++k) dst[m][k] = *(const LAS bf16x8*)(lds + PG8_SA(b, h) + aoff + m * 2048 + k * 1024); } while (0)
; #define PG8_LDB(dst, b, h) do { _Pragma("unroll") for (int n = 0; n < 2; ++n) _Pragma("unroll") for (int k = 0; k < 2; ++k) dst[n][k] = *(const LAS bf16x8*)(lds + PG8_SB(b, h) + boff + n * 2048 + k * 1024); } while (0)
; #define PG8_MMA(ai, bj, At, Bt) do { __builtin_amdgcn_s_setprio(1); _Pragma("unroll") for (int m = 0; m < 4; ++m) _Pragma("unroll") for (int n = 0; n < 2; ++n) _Pragma("unroll") for (int k = 0; k < 2; ++k) \
;         acc[ai][bj][m][n] = __builtin_amdgcn_mfma_f32_16x16x32_bf16(Bt[n][k], At[m][k], acc[ai][bj][m][n], 0, 0, 0); __builtin_amdgcn_s_setprio(0); } while (0)
; #define PG8_WAIT_V(n) asm volatile("s_waitcnt vmcnt(" #n ")" ::: "memory")
; #define PG8_WAIT_L(n) asm volatile("s_waitcnt lgkmcnt(" #n ")" ::: "memory")
; #define PG8_BAR __builtin_amdgcn_s_barrier()
; #define PG8_SCHED __builtin_amdgcn_sched_barrier(0)
; template <class Epi>
; DI void gemm_phase(LAS unsigned char* lds, const Gemm g, const StaticOrder S, const Epi E) {
;     ...
;             PG8_WAIT_V(8); PG8_WAIT_L(0); PG8_BAR; PG8_MMA(1, 0, At, B0); PG8_MMA(1, 1, At, B1); PG8_BAR; PG8_SCHED;
;             PG8_LDB(B0, 1, 0); PG8_LDB(B1, 1, 1); PG8_SCHED; PG8_LDA(At, 1, 0); PG8_STAGE(PG8_SA(0, 1), a2 + hstepA, voffA);
;             PG8_WAIT_V(8); PG8_WAIT_L(0); PG8_BAR; PG8_MMA(0, 0, At, B0); PG8_MMA(0, 1, At, B1); PG8_BAR; PG8_SCHED;
	s_setprio 1
	s_waitcnt lgkmcnt(0)
	v_mfma_f32_16x16x32_bf16 v[60:63], v[128:131], v[190:193], v[60:63]
	v_mfma_f32_16x16x32_bf16 v[56:59], v[136:139], v[190:193], v[56:59]
	v_mfma_f32_16x16x32_bf16 v[44:47], v[128:131], v[220:223], v[44:47]
	v_mfma_f32_16x16x32_bf16 v[40:43], v[136:139], v[220:223], v[40:43]
	v_mfma_f32_16x16x32_bf16 v[28:31], v[128:131], v[234:237], v[28:31]
	v_mfma_f32_16x16x32_bf16 v[24:27], v[136:139], v[234:237], v[24:27]
	v_mfma_f32_16x16x32_bf16 v[12:15], v[128:131], v[242:245], v[12:15]
	v_mfma_f32_16x16x32_bf16 v[8:11], v[136:139], v[242:245], v[8:11]
	v_mfma_f32_16x16x32_bf16 v[60:63], v[132:135], v[194:197], v[60:63]
	v_mfma_f32_16x16x32_bf16 v[56:59], v[140:143], v[194:197], v[56:59]
	v_mfma_f32_16x16x32_bf16 v[44:47], v[132:135], v[230:233], v[44:47]
	v_mfma_f32_16x16x32_bf16 v[40:43], v[140:143], v[230:233], v[40:43]
	v_mfma_f32_16x16x32_bf16 v[28:31], v[132:135], v[238:241], v[28:31]
	v_mfma_f32_16x16x32_bf16 v[24:27], v[140:143], v[238:241], v[24:27]
	v_mfma_f32_16x16x32_bf16 v[12:15], v[132:135], v[246:249], v[12:15]
	v_mfma_f32_16x16x32_bf16 v[8:11], v[140:143], v[246:249], v[8:11]
	s_setprio 0
	s_setprio 1
	v_mfma_f32_16x16x32_bf16 v[52:55], v[170:173], v[190:193], v[52:55]
	v_mfma_f32_16x16x32_bf16 v[48:51], v[178:181], v[190:193], v[48:51]
	v_mfma_f32_16x16x32_bf16 v[36:39], v[170:173], v[220:223], v[36:39]
	v_mfma_f32_16x16x32_bf16 v[32:35], v[178:181], v[220:223], v[32:35]
	v_mfma_f32_16x16x32_bf16 v[20:23], v[170:173], v[234:237], v[20:23]
	v_mfma_f32_16x16x32_bf16 v[16:19], v[178:181], v[234:237], v[16:19]
	v_mfma_f32_16x16x32_bf16 v[4:7], v[170:173], v[242:245], v[4:7]
	v_mfma_f32_16x16x32_bf16 v[0:3], v[178:181], v[242:245], v[0:3]
	v_mfma_f32_16x16x32_bf16 v[52:55], v[174:177], v[194:197], v[52:55]
	v_mfma_f32_16x16x32_bf16 v[48:51], v[186:189], v[194:197], v[48:51]
	v_mfma_f32_16x16x32_bf16 v[36:39], v[174:177], v[230:233], v[36:39]
	v_mfma_f32_16x16x32_bf16 v[32:35], v[186:189], v[230:233], v[32:35]
	v_mfma_f32_16x16x32_bf16 v[20:23], v[174:177], v[238:241], v[20:23]
	v_mfma_f32_16x16x32_bf16 v[16:19], v[186:189], v[238:241], v[16:19]
	v_mfma_f32_16x16x32_bf16 v[4:7], v[174:177], v[246:249], v[4:7]
	v_mfma_f32_16x16x32_bf16 v[0:3], v[186:189], v[246:249], v[0:3]
	s_setprio 0
	s_barrier
	s_add_i32 s26, 0, 0x1c000
	v_add_u32_e32 v140, s74, v183
	v_add_u32_e32 v146, s26, v183
	ds_read_b128 v[128:131], v140
	ds_read_b128 v[132:135], v140 offset:1024
	ds_read_b128 v[136:139], v140 offset:2048
	ds_read_b128 v[140:143], v140 offset:3072
	ds_read_b128 v[170:173], v146
	ds_read_b128 v[174:177], v146 offset:1024
	ds_read_b128 v[178:181], v146 offset:2048
	ds_read_b128 v[186:189], v146 offset:3072
	s_add_u32 s20, s60, 0x40000
	s_addc_u32 s21, s61, 0
	s_mov_b32 m0, s68
	ds_read_b128 v[190:193], v184 offset:32768
	ds_read_b128 v[194:197], v184 offset:33792
	ds_read_b128 v[220:223], v184 offset:34816
	ds_read_b128 v[230:233], v184 offset:35840
	ds_read_b128 v[234:237], v184 offset:36864
	ds_read_b128 v[238:241], v184 offset:37888
	ds_read_b128 v[242:245], v184 offset:38912
	ds_read_b128 v[246:249], v184 offset:39936
	global_load_lds_dwordx4 v158, s[20:21]
	s_mov_b32 m0, s69
	s_nop 0
	global_load_lds_dwordx4 v162, s[20:21]
	s_waitcnt vmcnt(8)
	s_waitcnt lgkmcnt(0)
	s_barrier
	s_setprio 1
	s_waitcnt lgkmcnt(0)
	v_mfma_f32_16x16x32_bf16 v[124:127], v[128:131], v[190:193], v[124:127]
	v_mfma_f32_16x16x32_bf16 v[120:123], v[136:139], v[190:193], v[120:123]
	v_mfma_f32_16x16x32_bf16 v[108:111], v[128:131], v[220:223], v[108:111]
	v_mfma_f32_16x16x32_bf16 v[104:107], v[136:139], v[220:223], v[104:107]
	v_mfma_f32_16x16x32_bf16 v[92:95], v[128:131], v[234:237], v[92:95]
	v_mfma_f32_16x16x32_bf16 v[88:91], v[136:139], v[234:237], v[88:91]
	v_mfma_f32_16x16x32_bf16 v[76:79], v[128:131], v[242:245], v[76:79]
	v_mfma_f32_16x16x32_bf16 v[72:75], v[136:139], v[242:245], v[72:75]
	v_mfma_f32_16x16x32_bf16 v[124:127], v[132:135], v[194:197], v[124:127]
	v_mfma_f32_16x16x32_bf16 v[120:123], v[140:143], v[194:197], v[120:123]
	v_mfma_f32_16x16x32_bf16 v[108:111], v[132:135], v[230:233], v[108:111]
	v_mfma_f32_16x16x32_bf16 v[104:107], v[140:143], v[230:233], v[104:107]
	v_mfma_f32_16x16x32_bf16 v[92:95], v[132:135], v[238:241], v[92:95]
	v_mfma_f32_16x16x32_bf16 v[88:91], v[140:143], v[238:241], v[88:91]
	v_mfma_f32_16x16x32_bf16 v[76:79], v[132:135], v[246:249], v[76:79]
	v_mfma_f32_16x16x32_bf16 v[72:75], v[140:143], v[246:249], v[72:75]
	s_setprio 0
	s_setprio 1
	v_mfma_f32_16x16x32_bf16 v[116:119], v[170:173], v[190:193], v[116:119]
	v_mfma_f32_16x16x32_bf16 v[112:115], v[178:181], v[190:193], v[112:115]
	v_mfma_f32_16x16x32_bf16 v[100:103], v[170:173], v[220:223], v[100:103]
	v_mfma_f32_16x16x32_bf16 v[96:99], v[178:181], v[220:223], v[96:99]
	v_mfma_f32_16x16x32_bf16 v[84:87], v[170:173], v[234:237], v[84:87]
	v_mfma_f32_16x16x32_bf16 v[80:83], v[178:181], v[234:237], v[80:83]
	v_mfma_f32_16x16x32_bf16 v[68:71], v[170:173], v[242:245], v[68:71]
	v_mfma_f32_16x16x32_bf16 v[64:67], v[178:181], v[242:245], v[64:67]
	v_mfma_f32_16x16x32_bf16 v[116:119], v[174:177], v[194:197], v[116:119]
	v_mfma_f32_16x16x32_bf16 v[112:115], v[186:189], v[194:197], v[112:115]
	v_mfma_f32_16x16x32_bf16 v[100:103], v[174:177], v[230:233], v[100:103]
	v_mfma_f32_16x16x32_bf16 v[96:99], v[186:189], v[230:233], v[96:99]
	v_mfma_f32_16x16x32_bf16 v[84:87], v[174:177], v[238:241], v[84:87]
	v_mfma_f32_16x16x32_bf16 v[80:83], v[186:189], v[238:241], v[80:83]
	v_mfma_f32_16x16x32_bf16 v[68:71], v[174:177], v[246:249], v[68:71]
	v_mfma_f32_16x16x32_bf16 v[64:67], v[186:189], v[246:249], v[64:67]
	s_setprio 0
	s_barrier
; #define PG8_STAGE(bufoff, gbase, voff) do { _Pragma("unroll") for (int _i = 0; _i < 2; ++_i) \
;         __builtin_amdgcn_global_load_lds((const unsigned*)((const char*)(gbase) + (voff)[_i]), (LAS unsigned*)(lds + (bufoff) + ldsw + _i * 8192), 16, 0, 0); } while (0)
; #define PG8_LDA(dst, b, h) do { _Pragma("unroll") for (int m = 0; m < 4; ++m) _Pragma("unroll") for (int k = 0; k < 2; ++k) dst[m][k] = *(const LAS bf16x8*)(lds + PG8_SA(b, h) + aoff + m * 2048 + k * 1024); } while (0)
; #define PG8_MMA(ai, bj, At, Bt) do { __builtin_amdgcn_s_setprio(1); _Pragma("unroll") for (int m = 0; m < 4; ++m) _Pragma("unroll") for (int n = 0; n < 2; ++n) _Pragma("unroll") for (int k = 0; k < 2; ++k) \
;         acc[ai][bj][m][n] = __builtin_amdgcn_mfma_f32_16x16x32_bf16(Bt[n][k], At[m][k], acc[ai][bj][m][n], 0, 0, 0); __builtin_amdgcn_s_setprio(0); } while (0)
; #define PG8_WAIT_V(n) asm volatile("s_waitcnt vmcnt(" #n ")" ::: "memory")
; #define PG8_WAIT_L(n) asm volatile("s_waitcnt lgkmcnt(" #n ")" ::: "memory")
; #define PG8_BAR __builtin_amdgcn_s_barrier()
; #define PG8_SCHED __builtin_amdgcn_sched_barrier(0)
; template <class Epi>
; DI void gemm_phase(LAS unsigned char* lds, const Gemm g, const StaticOrder S, const Epi E) {
;     ...
;             PG8_LDA(At, 1, 1); PG8_STAGE(PG8_SB(1, 0), b3, voffB); PG8_STAGE(PG8_SB(1, 1), b3 + hstepB, voffB); PG8_STAGE(PG8_SA(1, 0), a3, voffA);
;             PG8_WAIT_V(8); PG8_WAIT_L(0); PG8_BAR; PG8_MMA(1, 0, At, B0); PG8_MMA(1, 1, At, B1); PG8_BAR; PG8_SCHED;
;         }
	s_add_i32 s20, s74, s62
	s_mov_b32 m0, s20
	ds_read_b128 v[190:193], v184 offset:49152
	ds_read_b128 v[194:197], v184 offset:50176
	ds_read_b128 v[220:223], v184 offset:51200
	ds_read_b128 v[230:233], v184 offset:52224
	ds_read_b128 v[234:237], v184 offset:53248
	ds_read_b128 v[238:241], v184 offset:54272
	ds_read_b128 v[242:245], v184 offset:55296
	ds_read_b128 v[246:249], v184 offset:56320
	global_load_lds_dwordx4 v160, s[98:99]
	s_add_i32 m0, s20, 0x2000
	s_add_u32 s20, s30, 0x40080
	s_addc_u32 s21, s31, 0
	s_add_i32 s26, s26, s62
	global_load_lds_dwordx4 v164, s[98:99]
	s_mov_b32 m0, s26
	s_nop 0
	global_load_lds_dwordx4 v160, s[20:21]
	s_add_i32 m0, s26, 0x2000
	s_nop 0
	global_load_lds_dwordx4 v164, s[20:21]
	s_mov_b32 m0, s72
	s_nop 0
	global_load_lds_dwordx4 v158, s[100:101]
	s_mov_b32 m0, s73
	s_nop 0
	global_load_lds_dwordx4 v162, s[100:101]
	s_waitcnt vmcnt(8)
	s_waitcnt lgkmcnt(0)
	s_barrier
	s_setprio 1
	s_waitcnt lgkmcnt(0)
	v_mfma_f32_16x16x32_bf16 v[60:63], v[128:131], v[190:193], v[60:63]
	v_mfma_f32_16x16x32_bf16 v[56:59], v[136:139], v[190:193], v[56:59]
	v_mfma_f32_16x16x32_bf16 v[44:47], v[128:131], v[220:223], v[44:47]
	v_mfma_f32_16x16x32_bf16 v[40:43], v[136:139], v[220:223], v[40:43]
	v_mfma_f32_16x16x32_bf16 v[28:31], v[128:131], v[234:237], v[28:31]
	v_mfma_f32_16x16x32_bf16 v[24:27], v[136:139], v[234:237], v[24:27]
	v_mfma_f32_16x16x32_bf16 v[12:15], v[128:131], v[242:245], v[12:15]
	v_mfma_f32_16x16x32_bf16 v[8:11], v[136:139], v[242:245], v[8:11]
	v_mfma_f32_16x16x32_bf16 v[60:63], v[132:135], v[194:197], v[60:63]
	v_mfma_f32_16x16x32_bf16 v[56:59], v[140:143], v[194:197], v[56:59]
	v_mfma_f32_16x16x32_bf16 v[44:47], v[132:135], v[230:233], v[44:47]
	v_mfma_f32_16x16x32_bf16 v[40:43], v[140:143], v[230:233], v[40:43]
	v_mfma_f32_16x16x32_bf16 v[28:31], v[132:135], v[238:241], v[28:31]
	v_mfma_f32_16x16x32_bf16 v[24:27], v[140:143], v[238:241], v[24:27]
	v_mfma_f32_16x16x32_bf16 v[12:15], v[132:135], v[246:249], v[12:15]
	v_mfma_f32_16x16x32_bf16 v[8:11], v[140:143], v[246:249], v[8:11]
	s_setprio 0
	s_setprio 1
	v_mfma_f32_16x16x32_bf16 v[52:55], v[170:173], v[190:193], v[52:55]
	v_mfma_f32_16x16x32_bf16 v[48:51], v[178:181], v[190:193], v[48:51]
	v_mfma_f32_16x16x32_bf16 v[36:39], v[170:173], v[220:223], v[36:39]
	v_mfma_f32_16x16x32_bf16 v[32:35], v[178:181], v[220:223], v[32:35]
	v_mfma_f32_16x16x32_bf16 v[20:23], v[170:173], v[234:237], v[20:23]
	v_mfma_f32_16x16x32_bf16 v[16:19], v[178:181], v[234:237], v[16:19]
	v_mfma_f32_16x16x32_bf16 v[4:7], v[170:173], v[242:245], v[4:7]
	v_mfma_f32_16x16x32_bf16 v[0:3], v[178:181], v[242:245], v[0:3]
	v_mfma_f32_16x16x32_bf16 v[52:55], v[174:177], v[194:197], v[52:55]
	v_mfma_f32_16x16x32_bf16 v[48:51], v[186:189], v[194:197], v[48:51]
	v_mfma_f32_16x16x32_bf16 v[36:39], v[174:177], v[230:233], v[36:39]
	v_mfma_f32_16x16x32_bf16 v[32:35], v[186:189], v[230:233], v[32:35]
	v_mfma_f32_16x16x32_bf16 v[20:23], v[174:177], v[238:241], v[20:23]
	v_mfma_f32_16x16x32_bf16 v[16:19], v[186:189], v[238:241], v[16:19]
	v_mfma_f32_16x16x32_bf16 v[4:7], v[174:177], v[246:249], v[4:7]
	v_mfma_f32_16x16x32_bf16 v[0:3], v[186:189], v[246:249], v[0:3]
	s_setprio 0
	s_barrier
	s_add_i32 s79, s79, 2
	s_add_u32 s44, s44, 0x100
	s_addc_u32 s45, s45, 0
	s_add_u32 s49, s49, 0x100
	s_addc_u32 s51, s51, 0
	s_cmp_gt_u32 s79, 13
	s_cbranch_scc0 .LBB0_241
	s_and_b64 vcc, exec, s[46:47]
	s_cbranch_vccz .LBB0_244
	s_barrier

; #define PG8_STAGE(bufoff, gbase, voff) do { _Pragma("unroll") for (int _i = 0; _i < 2; ++_i) \
;         __builtin_amdgcn_global_load_lds((const unsigned*)((const char*)(gbase) + (voff)[_i]), (LAS unsigned*)(lds + (bufoff) + ldsw + _i * 8192), 16, 0, 0); } while (0)
; #define PG8_LDA(dst, b, h) do { _Pragma("unroll") for (int m = 0; m < 4; ++m) _Pragma("unroll") for (int k = 0; k < 2; ++k) dst[m][k] = *(const LAS bf16x8*)(lds + PG8_SA(b, h) + aoff + m * 2048 + k * 1024); } while (0)
; #define PG8_LDB(dst, b, h) do { _Pragma("unroll") for (int n = 0; n < 2; ++n) _Pragma("unroll") for (int k = 0; k < 2; ++k) dst[n][k] = *(const LAS bf16x8*)(lds + PG8_SB(b, h) + boff + n * 2048 + k * 1024); } while (0)
; #define PG8_MMA(ai, bj, At, Bt) do { __builtin_amdgcn_s_setprio(1); _Pragma("unroll") for (int m = 0; m < 4; ++m) _Pragma("unroll") for (int n = 0; n < 2; ++n) _Pragma("unroll") for (int k = 0; k < 2; ++k) \
;         acc[ai][bj][m][n] = __builtin_amdgcn_mfma_f32_16x16x32_bf16(Bt[n][k], At[m][k], acc[ai][bj][m][n], 0, 0, 0); __builtin_amdgcn_s_setprio(0); } while (0)
; #define PG8_WAIT_V(n) asm volatile("s_waitcnt vmcnt(" #n ")" ::: "memory")
; #define PG8_WAIT_L(n) asm volatile("s_waitcnt lgkmcnt(" #n ")" ::: "memory")
; #define PG8_BAR __builtin_amdgcn_s_barrier()
; #define PG8_SCHED __builtin_amdgcn_sched_barrier(0)
; template <class Epi>
; DI void gemm_phase(LAS unsigned char* lds, const Gemm g, const StaticOrder S, const Epi E) {
;     ...
;             const bool last = (t == nt - 2);
;             const char* a1 = cA + (size_t)(t + 1) * kstep;
;             const char* a2 = last ? nA : cA + (size_t)(t + 2) * kstep; const char* b2 = last ? nB : cB + (size_t)(t + 2) * kstep;
;             const char* a3 = a2 + kstep; const char* b3 = b2 + kstep;
;             PG8_LDB(B0, 0, 0); PG8_LDB(B1, 0, 1); PG8_SCHED; PG8_LDA(At, 0, 0); PG8_STAGE(PG8_SA(1, 1), a1 + hstepA, voffA);
;             PG8_WAIT_V(8); PG8_WAIT_L(0); PG8_BAR; PG8_MMA(0, 0, At, B0); PG8_MMA(0, 1, At, B1); PG8_BAR; PG8_SCHED;
;             PG8_LDA(At, 0, 1); PG8_STAGE(PG8_SB(0, 0), b2, voffB); PG8_STAGE(PG8_SB(0, 1), b2 + hstepB, voffB); PG8_STAGE(PG8_SA(0, 0), a2, voffA);
.LBB0_290:
	s_add_u32 s20, s54, 0xfffc0080
	s_addc_u32 s21, s55, -1
	s_add_i32 s26, 0, 0x10000
	s_cmp_eq_u32 s72, 12
	s_cselect_b32 s57, s43, s21
	s_cselect_b32 s56, s42, s20
	v_add_u32_e32 v140, s26, v145
	s_cselect_b32 s31, s51, s47
	s_cselect_b32 s30, s50, s45
	s_add_u32 s98, s30, 0x80
	s_addc_u32 s99, s31, 0
	s_add_u32 s100, s56, 0x80
	s_addc_u32 s101, s57, 0
	s_add_i32 s27, 0, 0x14000
	ds_read_b128 v[158:161], v140
	ds_read_b128 v[162:165], v140 offset:1024
	ds_read_b128 v[166:169], v140 offset:2048
	ds_read_b128 v[170:173], v140 offset:3072
	v_add_u32_e32 v140, s27, v145
	ds_read_b128 v[174:177], v140
	ds_read_b128 v[178:181], v140 offset:1024
	ds_read_b128 v[182:185], v140 offset:2048
	ds_read_b128 v[186:189], v140 offset:3072
	s_add_i32 m0, s49, 0xc000
	ds_read_b128 v[190:193], v157
	ds_read_b128 v[194:197], v157 offset:1024
	ds_read_b128 v[220:223], v157 offset:2048
	ds_read_b128 v[230:233], v157 offset:3072
	ds_read_b128 v[234:237], v157 offset:4096
	ds_read_b128 v[238:241], v157 offset:5120
	ds_read_b128 v[242:245], v157 offset:6144
	ds_read_b128 v[246:249], v157 offset:7168
	global_load_lds_dwordx4 v136, s[54:55]
	s_add_i32 m0, s49, 0xe000
	s_nop 0
	global_load_lds_dwordx4 v138, s[54:55]
	s_waitcnt vmcnt(8)
	s_waitcnt lgkmcnt(0)
	s_barrier
	s_setprio 1
	s_waitcnt lgkmcnt(0)
	v_mfma_f32_16x16x32_bf16 v[124:127], v[158:161], v[190:193], v[124:127]
	v_mfma_f32_16x16x32_bf16 v[120:123], v[166:169], v[190:193], v[120:123]
	v_mfma_f32_16x16x32_bf16 v[116:119], v[158:161], v[220:223], v[116:119]
	v_mfma_f32_16x16x32_bf16 v[108:111], v[166:169], v[220:223], v[108:111]
	v_mfma_f32_16x16x32_bf16 v[100:103], v[158:161], v[234:237], v[100:103]
	v_mfma_f32_16x16x32_bf16 v[92:95], v[166:169], v[234:237], v[92:95]
	v_mfma_f32_16x16x32_bf16 v[84:87], v[158:161], v[242:245], v[84:87]
	v_mfma_f32_16x16x32_bf16 v[76:79], v[166:169], v[242:245], v[76:79]
	v_mfma_f32_16x16x32_bf16 v[124:127], v[162:165], v[194:197], v[124:127]
	v_mfma_f32_16x16x32_bf16 v[120:123], v[170:173], v[194:197], v[120:123]
	v_mfma_f32_16x16x32_bf16 v[116:119], v[162:165], v[230:233], v[116:119]
	v_mfma_f32_16x16x32_bf16 v[108:111], v[170:173], v[230:233], v[108:111]
	v_mfma_f32_16x16x32_bf16 v[100:103], v[162:165], v[238:241], v[100:103]
	v_mfma_f32_16x16x32_bf16 v[92:95], v[170:173], v[238:241], v[92:95]
	v_mfma_f32_16x16x32_bf16 v[84:87], v[162:165], v[246:249], v[84:87]
	v_mfma_f32_16x16x32_bf16 v[76:79], v[170:173], v[246:249], v[76:79]
	s_setprio 0
	s_setprio 1
	v_mfma_f32_16x16x32_bf16 v[112:115], v[174:177], v[190:193], v[112:115]
	v_mfma_f32_16x16x32_bf16 v[104:107], v[182:185], v[190:193], v[104:107]
	v_mfma_f32_16x16x32_bf16 v[96:99], v[174:177], v[220:223], v[96:99]
	v_mfma_f32_16x16x32_bf16 v[88:91], v[182:185], v[220:223], v[88:91]
	v_mfma_f32_16x16x32_bf16 v[80:83], v[174:177], v[234:237], v[80:83]
	v_mfma_f32_16x16x32_bf16 v[72:75], v[182:185], v[234:237], v[72:75]
	v_mfma_f32_16x16x32_bf16 v[68:71], v[174:177], v[242:245], v[68:71]
	v_mfma_f32_16x16x32_bf16 v[64:67], v[182:185], v[242:245], v[64:67]
	v_mfma_f32_16x16x32_bf16 v[112:115], v[178:181], v[194:197], v[112:115]
	v_mfma_f32_16x16x32_bf16 v[104:107], v[186:189], v[194:197], v[104:107]
	v_mfma_f32_16x16x32_bf16 v[96:99], v[178:181], v[230:233], v[96:99]
	v_mfma_f32_16x16x32_bf16 v[88:91], v[186:189], v[230:233], v[88:91]
	v_mfma_f32_16x16x32_bf16 v[80:83], v[178:181], v[238:241], v[80:83]
	v_mfma_f32_16x16x32_bf16 v[72:75], v[186:189], v[238:241], v[72:75]
	v_mfma_f32_16x16x32_bf16 v[68:71], v[178:181], v[246:249], v[68:71]
	v_mfma_f32_16x16x32_bf16 v[64:67], v[186:189], v[246:249], v[64:67]
	s_setprio 0
	s_barrier
	s_add_i32 s20, s26, s58
	s_mov_b32 m0, s20
	ds_read_b128 v[190:193], v157 offset:16384
	ds_read_b128 v[194:197], v157 offset:17408
	ds_read_b128 v[220:223], v157 offset:18432
	ds_read_b128 v[230:233], v157 offset:19456
	ds_read_b128 v[234:237], v157 offset:20480
	ds_read_b128 v[238:241], v157 offset:21504
	ds_read_b128 v[242:245], v157 offset:22528
	ds_read_b128 v[246:249], v157 offset:23552
	global_load_lds_dwordx4 v130, s[30:31]
	s_add_i32 m0, s20, 0x2000
	s_add_u32 s20, s30, 0x40000
	s_addc_u32 s21, s31, 0
	s_add_i32 s26, s27, s58
	global_load_lds_dwordx4 v134, s[30:31]
	s_mov_b32 m0, s26
	s_nop 0
	global_load_lds_dwordx4 v130, s[20:21]
	s_add_i32 m0, s26, 0x2000
	s_nop 0
	global_load_lds_dwordx4 v134, s[20:21]
	s_mov_b32 m0, s49
	s_nop 0
	global_load_lds_dwordx4 v128, s[56:57]
	s_mov_b32 m0, s53
	s_nop 0
	global_load_lds_dwordx4 v132, s[56:57]
	s_waitcnt vmcnt(8)
	s_waitcnt lgkmcnt(0)
	s_barrier
; #define PG8_STAGE(bufoff, gbase, voff) do { _Pragma("unroll") for (int _i = 0; _i < 2; ++_i) \
;         __builtin_amdgcn_global_load_lds((const unsigned*)((const char*)(gbase) + (voff)[_i]), (LAS unsigned*)(lds + (bufoff) + ldsw + _i * 8192), 16, 0, 0); } while (0)
; #define PG8_LDA(dst, b, h) do { _Pragma("unroll") for (int m = 0; m < 4; ++m) _Pragma("unroll") for (int k = 0; k < 2; ++k) dst[m][k] = *(const LAS bf16x8*)(lds + PG8_SA(b, h) + aoff + m * 2048 + k * 1024); } while (0)
; #define PG8_LDB(dst, b, h) do { _Pragma("unroll") for (int n = 0; n < 2; ++n) _Pragma("unroll") for (int k = 0; k < 2; ++k) dst[n][k] = *(const LAS bf16x8*)(lds + PG8_SB(b, h) + boff + n * 2048 + k * 1024); } while (0)
; #define PG8_MMA(ai, bj, At, Bt) do { __builtin_amdgcn_s_setprio(1); _Pragma("unroll") for (int m = 0; m < 4; ++m) _Pragma("unroll") for (int n = 0; n < 2; ++n) _Pragma("unroll") for (int k = 0; k < 2; ++k) \
;         acc[ai][bj][m][n] = __builtin_amdgcn_mfma_f32_16x16x32_bf16(Bt[n][k], At[m][k], acc[ai][bj][m][n], 0, 0, 0); __builtin_amdgcn_s_setprio(0); } while (0)
; #define PG8_WAIT_V(n) asm volatile("s_waitcnt vmcnt(" #n ")" ::: "memory")
; #define PG8_WAIT_L(n) asm volatile("s_waitcnt lgkmcnt(" #n ")" ::: "memory")
; #define PG8_BAR __builtin_amdgcn_s_barrier()
; #define PG8_SCHED __builtin_amdgcn_sched_barrier(0)
; template <class Epi>
; DI void gemm_phase(LAS unsigned char* lds, const Gemm g, const StaticOrder S, const Epi E) {
;     ...
;             PG8_WAIT_V(8); PG8_WAIT_L(0); PG8_BAR; PG8_MMA(1, 0, At, B0); PG8_MMA(1, 1, At, B1); PG8_BAR; PG8_SCHED;
;             PG8_LDB(B0, 1, 0); PG8_LDB(B1, 1, 1); PG8_SCHED; PG8_LDA(At, 1, 0); PG8_STAGE(PG8_SA(0, 1), a2 + hstepA, voffA);
;             PG8_WAIT_V(8); PG8_WAIT_L(0); PG8_BAR; PG8_MMA(0, 0, At, B0); PG8_MMA(0, 1, At, B1); PG8_BAR; PG8_SCHED;
	s_setprio 1
	s_waitcnt lgkmcnt(0)
	v_mfma_f32_16x16x32_bf16 v[60:63], v[158:161], v[190:193], v[60:63]
	v_mfma_f32_16x16x32_bf16 v[56:59], v[166:169], v[190:193], v[56:59]
	v_mfma_f32_16x16x32_bf16 v[52:55], v[158:161], v[220:223], v[52:55]
	v_mfma_f32_16x16x32_bf16 v[44:47], v[166:169], v[220:223], v[44:47]
	v_mfma_f32_16x16x32_bf16 v[36:39], v[158:161], v[234:237], v[36:39]
	v_mfma_f32_16x16x32_bf16 v[28:31], v[166:169], v[234:237], v[28:31]
	v_mfma_f32_16x16x32_bf16 v[20:23], v[158:161], v[242:245], v[20:23]
	v_mfma_f32_16x16x32_bf16 v[12:15], v[166:169], v[242:245], v[12:15]
	v_mfma_f32_16x16x32_bf16 v[60:63], v[162:165], v[194:197], v[60:63]
	v_mfma_f32_16x16x32_bf16 v[56:59], v[170:173], v[194:197], v[56:59]
	v_mfma_f32_16x16x32_bf16 v[52:55], v[162:165], v[230:233], v[52:55]
	v_mfma_f32_16x16x32_bf16 v[44:47], v[170:173], v[230:233], v[44:47]
	v_mfma_f32_16x16x32_bf16 v[36:39], v[162:165], v[238:241], v[36:39]
	v_mfma_f32_16x16x32_bf16 v[28:31], v[170:173], v[238:241], v[28:31]
	v_mfma_f32_16x16x32_bf16 v[20:23], v[162:165], v[246:249], v[20:23]
	v_mfma_f32_16x16x32_bf16 v[12:15], v[170:173], v[246:249], v[12:15]
	s_setprio 0
	s_setprio 1
	v_mfma_f32_16x16x32_bf16 v[48:51], v[174:177], v[190:193], v[48:51]
	v_mfma_f32_16x16x32_bf16 v[40:43], v[182:185], v[190:193], v[40:43]
	v_mfma_f32_16x16x32_bf16 v[32:35], v[174:177], v[220:223], v[32:35]
	v_mfma_f32_16x16x32_bf16 v[24:27], v[182:185], v[220:223], v[24:27]
	v_mfma_f32_16x16x32_bf16 v[16:19], v[174:177], v[234:237], v[16:19]
	v_mfma_f32_16x16x32_bf16 v[8:11], v[182:185], v[234:237], v[8:11]
	v_mfma_f32_16x16x32_bf16 v[4:7], v[174:177], v[242:245], v[4:7]
	v_mfma_f32_16x16x32_bf16 v[0:3], v[182:185], v[242:245], v[0:3]
	v_mfma_f32_16x16x32_bf16 v[48:51], v[178:181], v[194:197], v[48:51]
	v_mfma_f32_16x16x32_bf16 v[40:43], v[186:189], v[194:197], v[40:43]
	v_mfma_f32_16x16x32_bf16 v[32:35], v[178:181], v[230:233], v[32:35]
	v_mfma_f32_16x16x32_bf16 v[24:27], v[186:189], v[230:233], v[24:27]
	v_mfma_f32_16x16x32_bf16 v[16:19], v[178:181], v[238:241], v[16:19]
	v_mfma_f32_16x16x32_bf16 v[8:11], v[186:189], v[238:241], v[8:11]
	v_mfma_f32_16x16x32_bf16 v[4:7], v[178:181], v[246:249], v[4:7]
	v_mfma_f32_16x16x32_bf16 v[0:3], v[186:189], v[246:249], v[0:3]
	s_setprio 0
	s_barrier
	v_add_u32_e32 v140, s74, v145
	s_add_i32 s26, 0, 0x1c000
	ds_read_b128 v[158:161], v140
	ds_read_b128 v[162:165], v140 offset:1024
	ds_read_b128 v[166:169], v140 offset:2048
	ds_read_b128 v[170:173], v140 offset:3072
	v_add_u32_e32 v140, s26, v145
	ds_read_b128 v[174:177], v140
	ds_read_b128 v[178:181], v140 offset:1024
	ds_read_b128 v[182:185], v140 offset:2048
	ds_read_b128 v[186:189], v140 offset:3072
	s_add_u32 s20, s56, 0x40000
	s_addc_u32 s21, s57, 0
	s_mov_b32 m0, s59
	ds_read_b128 v[190:193], v157 offset:32768
	ds_read_b128 v[194:197], v157 offset:33792
	ds_read_b128 v[220:223], v157 offset:34816
	ds_read_b128 v[230:233], v157 offset:35840
	ds_read_b128 v[234:237], v157 offset:36864
	ds_read_b128 v[238:241], v157 offset:37888
	ds_read_b128 v[242:245], v157 offset:38912
	ds_read_b128 v[246:249], v157 offset:39936
	global_load_lds_dwordx4 v128, s[20:21]
	s_mov_b32 m0, s60
	s_nop 0
	global_load_lds_dwordx4 v132, s[20:21]
	s_waitcnt vmcnt(8)
	s_waitcnt lgkmcnt(0)
	s_barrier
	s_setprio 1
	s_waitcnt lgkmcnt(0)
	v_mfma_f32_16x16x32_bf16 v[124:127], v[158:161], v[190:193], v[124:127]
	v_mfma_f32_16x16x32_bf16 v[120:123], v[166:169], v[190:193], v[120:123]
	v_mfma_f32_16x16x32_bf16 v[116:119], v[158:161], v[220:223], v[116:119]
	v_mfma_f32_16x16x32_bf16 v[108:111], v[166:169], v[220:223], v[108:111]
	v_mfma_f32_16x16x32_bf16 v[100:103], v[158:161], v[234:237], v[100:103]
	v_mfma_f32_16x16x32_bf16 v[92:95], v[166:169], v[234:237], v[92:95]
	v_mfma_f32_16x16x32_bf16 v[84:87], v[158:161], v[242:245], v[84:87]
	v_mfma_f32_16x16x32_bf16 v[76:79], v[166:169], v[242:245], v[76:79]
	v_mfma_f32_16x16x32_bf16 v[124:127], v[162:165], v[194:197], v[124:127]
	v_mfma_f32_16x16x32_bf16 v[120:123], v[170:173], v[194:197], v[120:123]
	v_mfma_f32_16x16x32_bf16 v[116:119], v[162:165], v[230:233], v[116:119]
	v_mfma_f32_16x16x32_bf16 v[108:111], v[170:173], v[230:233], v[108:111]
	v_mfma_f32_16x16x32_bf16 v[100:103], v[162:165], v[238:241], v[100:103]
	v_mfma_f32_16x16x32_bf16 v[92:95], v[170:173], v[238:241], v[92:95]
	v_mfma_f32_16x16x32_bf16 v[84:87], v[162:165], v[246:249], v[84:87]
	v_mfma_f32_16x16x32_bf16 v[76:79], v[170:173], v[246:249], v[76:79]
	s_setprio 0
	s_setprio 1
	v_mfma_f32_16x16x32_bf16 v[112:115], v[174:177], v[190:193], v[112:115]
	v_mfma_f32_16x16x32_bf16 v[104:107], v[182:185], v[190:193], v[104:107]
	v_mfma_f32_16x16x32_bf16 v[96:99], v[174:177], v[220:223], v[96:99]
	v_mfma_f32_16x16x32_bf16 v[88:91], v[182:185], v[220:223], v[88:91]
	v_mfma_f32_16x16x32_bf16 v[80:83], v[174:177], v[234:237], v[80:83]
	v_mfma_f32_16x16x32_bf16 v[72:75], v[182:185], v[234:237], v[72:75]
	v_mfma_f32_16x16x32_bf16 v[68:71], v[174:177], v[242:245], v[68:71]
	v_mfma_f32_16x16x32_bf16 v[64:67], v[182:185], v[242:245], v[64:67]
	v_mfma_f32_16x16x32_bf16 v[112:115], v[178:181], v[194:197], v[112:115]
	v_mfma_f32_16x16x32_bf16 v[104:107], v[186:189], v[194:197], v[104:107]
	v_mfma_f32_16x16x32_bf16 v[96:99], v[178:181], v[230:233], v[96:99]
	v_mfma_f32_16x16x32_bf16 v[88:91], v[186:189], v[230:233], v[88:91]
	v_mfma_f32_16x16x32_bf16 v[80:83], v[178:181], v[238:241], v[80:83]
	v_mfma_f32_16x16x32_bf16 v[72:75], v[186:189], v[238:241], v[72:75]
	v_mfma_f32_16x16x32_bf16 v[68:71], v[178:181], v[246:249], v[68:71]
	v_mfma_f32_16x16x32_bf16 v[64:67], v[186:189], v[246:249], v[64:67]
	s_setprio 0
	s_barrier
; #define PG8_STAGE(bufoff, gbase, voff) do { _Pragma("unroll") for (int _i = 0; _i < 2; ++_i) \
;         __builtin_amdgcn_global_load_lds((const unsigned*)((const char*)(gbase) + (voff)[_i]), (LAS unsigned*)(lds + (bufoff) + ldsw + _i * 8192), 16, 0, 0); } while (0)
; #define PG8_LDA(dst, b, h) do { _Pragma("unroll") for (int m = 0; m < 4; ++m) _Pragma("unroll") for (int k = 0; k < 2; ++k) dst[m][k] = *(const LAS bf16x8*)(lds + PG8_SA(b, h) + aoff + m * 2048 + k * 1024); } while (0)
; #define PG8_MMA(ai, bj, At, Bt) do { __builtin_amdgcn_s_setprio(1); _Pragma("unroll") for (int m = 0; m < 4; ++m) _Pragma("unroll") for (int n = 0; n < 2; ++n) _Pragma("unroll") for (int k = 0; k < 2; ++k) \
;         acc[ai][bj][m][n] = __builtin_amdgcn_mfma_f32_16x16x32_bf16(Bt[n][k], At[m][k], acc[ai][bj][m][n], 0, 0, 0); __builtin_amdgcn_s_setprio(0); } while (0)
; #define PG8_WAIT_V(n) asm volatile("s_waitcnt vmcnt(" #n ")" ::: "memory")
; #define PG8_WAIT_L(n) asm volatile("s_waitcnt lgkmcnt(" #n ")" ::: "memory")
; #define PG8_BAR __builtin_amdgcn_s_barrier()
; #define PG8_SCHED __builtin_amdgcn_sched_barrier(0)
; template <class Epi>
; DI void gemm_phase(LAS unsigned char* lds, const Gemm g, const StaticOrder S, const Epi E) {
;     ...
;             PG8_LDA(At, 1, 1); PG8_STAGE(PG8_SB(1, 0), b3, voffB); PG8_STAGE(PG8_SB(1, 1), b3 + hstepB, voffB); PG8_STAGE(PG8_SA(1, 0), a3, voffA);
;             PG8_WAIT_V(8); PG8_WAIT_L(0); PG8_BAR; PG8_MMA(1, 0, At, B0); PG8_MMA(1, 1, At, B1); PG8_BAR; PG8_SCHED;
;         }
	s_add_i32 s20, s74, s58
	s_mov_b32 m0, s20
	ds_read_b128 v[190:193], v157 offset:49152
	ds_read_b128 v[194:197], v157 offset:50176
	ds_read_b128 v[220:223], v157 offset:51200
	ds_read_b128 v[230:233], v157 offset:52224
	ds_read_b128 v[234:237], v157 offset:53248
	ds_read_b128 v[238:241], v157 offset:54272
	ds_read_b128 v[242:245], v157 offset:55296
	ds_read_b128 v[246:249], v157 offset:56320
	global_load_lds_dwordx4 v130, s[98:99]
	s_add_i32 m0, s20, 0x2000
	s_add_u32 s20, s30, 0x40080
	s_addc_u32 s21, s31, 0
	s_add_i32 s26, s26, s58
	global_load_lds_dwordx4 v134, s[98:99]
	s_mov_b32 m0, s26
	s_nop 0
	global_load_lds_dwordx4 v130, s[20:21]
	s_add_i32 m0, s26, 0x2000
	s_nop 0
	global_load_lds_dwordx4 v134, s[20:21]
	s_mov_b32 m0, s68
	s_nop 0
	global_load_lds_dwordx4 v128, s[100:101]
	s_mov_b32 m0, s69
	s_nop 0
	global_load_lds_dwordx4 v132, s[100:101]
	s_waitcnt vmcnt(8)
	s_waitcnt lgkmcnt(0)
	s_barrier
	s_setprio 1
	s_waitcnt lgkmcnt(0)
	v_mfma_f32_16x16x32_bf16 v[60:63], v[158:161], v[190:193], v[60:63]
	v_mfma_f32_16x16x32_bf16 v[56:59], v[166:169], v[190:193], v[56:59]
	v_mfma_f32_16x16x32_bf16 v[52:55], v[158:161], v[220:223], v[52:55]
	v_mfma_f32_16x16x32_bf16 v[44:47], v[166:169], v[220:223], v[44:47]
	v_mfma_f32_16x16x32_bf16 v[36:39], v[158:161], v[234:237], v[36:39]
	v_mfma_f32_16x16x32_bf16 v[28:31], v[166:169], v[234:237], v[28:31]
	v_mfma_f32_16x16x32_bf16 v[20:23], v[158:161], v[242:245], v[20:23]
	v_mfma_f32_16x16x32_bf16 v[12:15], v[166:169], v[242:245], v[12:15]
	v_mfma_f32_16x16x32_bf16 v[60:63], v[162:165], v[194:197], v[60:63]
	v_mfma_f32_16x16x32_bf16 v[56:59], v[170:173], v[194:197], v[56:59]
	v_mfma_f32_16x16x32_bf16 v[52:55], v[162:165], v[230:233], v[52:55]
	v_mfma_f32_16x16x32_bf16 v[44:47], v[170:173], v[230:233], v[44:47]
	v_mfma_f32_16x16x32_bf16 v[36:39], v[162:165], v[238:241], v[36:39]
	v_mfma_f32_16x16x32_bf16 v[28:31], v[170:173], v[238:241], v[28:31]
	v_mfma_f32_16x16x32_bf16 v[20:23], v[162:165], v[246:249], v[20:23]
	v_mfma_f32_16x16x32_bf16 v[12:15], v[170:173], v[246:249], v[12:15]
	s_setprio 0
	s_setprio 1
	v_mfma_f32_16x16x32_bf16 v[48:51], v[174:177], v[190:193], v[48:51]
	v_mfma_f32_16x16x32_bf16 v[40:43], v[182:185], v[190:193], v[40:43]
	v_mfma_f32_16x16x32_bf16 v[32:35], v[174:177], v[220:223], v[32:35]
	v_mfma_f32_16x16x32_bf16 v[24:27], v[182:185], v[220:223], v[24:27]
	v_mfma_f32_16x16x32_bf16 v[16:19], v[174:177], v[234:237], v[16:19]
	v_mfma_f32_16x16x32_bf16 v[8:11], v[182:185], v[234:237], v[8:11]
	v_mfma_f32_16x16x32_bf16 v[4:7], v[174:177], v[242:245], v[4:7]
	v_mfma_f32_16x16x32_bf16 v[0:3], v[182:185], v[242:245], v[0:3]
	v_mfma_f32_16x16x32_bf16 v[48:51], v[178:181], v[194:197], v[48:51]
	v_mfma_f32_16x16x32_bf16 v[40:43], v[186:189], v[194:197], v[40:43]
	v_mfma_f32_16x16x32_bf16 v[32:35], v[178:181], v[230:233], v[32:35]
	v_mfma_f32_16x16x32_bf16 v[24:27], v[186:189], v[230:233], v[24:27]
	v_mfma_f32_16x16x32_bf16 v[16:19], v[178:181], v[238:241], v[16:19]
	v_mfma_f32_16x16x32_bf16 v[8:11], v[186:189], v[238:241], v[8:11]
	v_mfma_f32_16x16x32_bf16 v[4:7], v[178:181], v[246:249], v[4:7]
	v_mfma_f32_16x16x32_bf16 v[0:3], v[186:189], v[246:249], v[0:3]
	s_setprio 0
	s_barrier
	s_add_i32 s72, s72, 2
	s_add_u32 s54, s54, 0x100
	s_addc_u32 s55, s55, 0
	s_add_u32 s45, s45, 0x100
	s_addc_u32 s47, s47, 0
	s_cmp_gt_u32 s72, 13
	s_cbranch_scc0 .LBB0_290
	s_and_b64 vcc, exec, s[22:23]
	s_cbranch_vccz .LBB0_293
	s_barrier

; #define PG8_STAGE(bufoff, gbase, voff) do { _Pragma("unroll") for (int _i = 0; _i < 2; ++_i) \
;         __builtin_amdgcn_global_load_lds((const unsigned*)((const char*)(gbase) + (voff)[_i]), (LAS unsigned*)(lds + (bufoff) + ldsw + _i * 8192), 16, 0, 0); } while (0)
; #define PG8_LDA(dst, b, h) do { _Pragma("unroll") for (int m = 0; m < 4; ++m) _Pragma("unroll") for (int k = 0; k < 2; ++k) dst[m][k] = *(const LAS bf16x8*)(lds + PG8_SA(b, h) + aoff + m * 2048 + k * 1024); } while (0)
; #define PG8_LDB(dst, b, h) do { _Pragma("unroll") for (int n = 0; n < 2; ++n) _Pragma("unroll") for (int k = 0; k < 2; ++k) dst[n][k] = *(const LAS bf16x8*)(lds + PG8_SB(b, h) + boff + n * 2048 + k * 1024); } while (0)
; #define PG8_MMA(ai, bj, At, Bt) do { __builtin_amdgcn_s_setprio(1); _Pragma("unroll") for (int m = 0; m < 4; ++m) _Pragma("unroll") for (int n = 0; n < 2; ++n) _Pragma("unroll") for (int k = 0; k < 2; ++k) \
;         acc[ai][bj][m][n] = __builtin_amdgcn_mfma_f32_16x16x32_bf16(Bt[n][k], At[m][k], acc[ai][bj][m][n], 0, 0, 0); __builtin_amdgcn_s_setprio(0); } while (0)
; #define PG8_WAIT_V(n) asm volatile("s_waitcnt vmcnt(" #n ")" ::: "memory")
; #define PG8_WAIT_L(n) asm volatile("s_waitcnt lgkmcnt(" #n ")" ::: "memory")
; #define PG8_BAR __builtin_amdgcn_s_barrier()
; #define PG8_SCHED __builtin_amdgcn_sched_barrier(0)
; template <class Epi>
; DI void gemm_phase(LAS unsigned char* lds, const Gemm g, const StaticOrder S, const Epi E) {
;     ...
;             const bool last = (t == nt - 2);
;             const char* a1 = cA + (size_t)(t + 1) * kstep;
;             const char* a2 = last ? nA : cA + (size_t)(t + 2) * kstep; const char* b2 = last ? nB : cB + (size_t)(t + 2) * kstep;
;             const char* a3 = a2 + kstep; const char* b3 = b2 + kstep;
;             PG8_LDB(B0, 0, 0); PG8_LDB(B1, 0, 1); PG8_SCHED; PG8_LDA(At, 0, 0); PG8_STAGE(PG8_SA(1, 1), a1 + hstepA, voffA);
;             PG8_WAIT_V(8); PG8_WAIT_L(0); PG8_BAR; PG8_MMA(0, 0, At, B0); PG8_MMA(0, 1, At, B1); PG8_BAR; PG8_SCHED;
;             PG8_LDA(At, 0, 1); PG8_STAGE(PG8_SB(0, 0), b2, voffB); PG8_STAGE(PG8_SB(0, 1), b2 + hstepB, voffB); PG8_STAGE(PG8_SA(0, 0), a2, voffA);
.LBB0_335:
	s_add_u32 s20, s42, 0xfffc0080
	s_addc_u32 s21, s43, -1
	s_add_i32 s26, 0, 0x10000
	s_cmp_eq_u32 s57, 12
	s_cselect_b32 s65, s59, s21
	s_cselect_b32 s64, s58, s20
	s_cselect_b32 s31, s61, s55
	s_cselect_b32 s30, s60, s3
	s_add_u32 s98, s30, 0x80
	s_addc_u32 s99, s31, 0
	s_add_u32 s100, s64, 0x80
	s_addc_u32 s101, s65, 0
	s_add_i32 s27, 0, 0x14000
	v_add_u32_e32 v140, s26, v220
	v_add_u32_e32 v146, s27, v220
	ds_read_b128 v[128:131], v140
	ds_read_b128 v[132:135], v140 offset:1024
	ds_read_b128 v[136:139], v140 offset:2048
	ds_read_b128 v[140:143], v140 offset:3072
	ds_read_b128 v[168:171], v146
	ds_read_b128 v[172:175], v146 offset:1024
	ds_read_b128 v[176:179], v146 offset:2048
	ds_read_b128 v[180:183], v146 offset:3072
	s_add_i32 m0, s76, 0xc000
	ds_read_b128 v[184:187], v221
	ds_read_b128 v[188:191], v221 offset:1024
	ds_read_b128 v[192:195], v221 offset:2048
	ds_read_b128 v[196:199], v221 offset:3072
	ds_read_b128 v[222:225], v221 offset:4096
	ds_read_b128 v[230:233], v221 offset:5120
	ds_read_b128 v[234:237], v221 offset:6144
	ds_read_b128 v[238:241], v221 offset:7168
	global_load_lds_dwordx4 v164, s[42:43]
	s_add_i32 m0, s76, 0xe000
	s_nop 0
	global_load_lds_dwordx4 v166, s[42:43]
	s_waitcnt vmcnt(8)
	s_waitcnt lgkmcnt(0)
	s_barrier
	s_setprio 1
	s_waitcnt lgkmcnt(0)
	v_mfma_f32_16x16x32_bf16 v[124:127], v[128:131], v[184:187], v[124:127]
	v_mfma_f32_16x16x32_bf16 v[120:123], v[136:139], v[184:187], v[120:123]
	v_mfma_f32_16x16x32_bf16 v[108:111], v[128:131], v[192:195], v[108:111]
	v_mfma_f32_16x16x32_bf16 v[104:107], v[136:139], v[192:195], v[104:107]
	v_mfma_f32_16x16x32_bf16 v[92:95], v[128:131], v[222:225], v[92:95]
	v_mfma_f32_16x16x32_bf16 v[88:91], v[136:139], v[222:225], v[88:91]
	v_mfma_f32_16x16x32_bf16 v[76:79], v[128:131], v[234:237], v[76:79]
	v_mfma_f32_16x16x32_bf16 v[72:75], v[136:139], v[234:237], v[72:75]
	v_mfma_f32_16x16x32_bf16 v[124:127], v[132:135], v[188:191], v[124:127]
	v_mfma_f32_16x16x32_bf16 v[120:123], v[140:143], v[188:191], v[120:123]
	v_mfma_f32_16x16x32_bf16 v[108:111], v[132:135], v[196:199], v[108:111]
	v_mfma_f32_16x16x32_bf16 v[104:107], v[140:143], v[196:199], v[104:107]
	v_mfma_f32_16x16x32_bf16 v[92:95], v[132:135], v[230:233], v[92:95]
	v_mfma_f32_16x16x32_bf16 v[88:91], v[140:143], v[230:233], v[88:91]
	v_mfma_f32_16x16x32_bf16 v[76:79], v[132:135], v[238:241], v[76:79]
	v_mfma_f32_16x16x32_bf16 v[72:75], v[140:143], v[238:241], v[72:75]
	s_setprio 0
	s_setprio 1
	v_mfma_f32_16x16x32_bf16 v[116:119], v[168:171], v[184:187], v[116:119]
	v_mfma_f32_16x16x32_bf16 v[112:115], v[176:179], v[184:187], v[112:115]
	v_mfma_f32_16x16x32_bf16 v[100:103], v[168:171], v[192:195], v[100:103]
	v_mfma_f32_16x16x32_bf16 v[96:99], v[176:179], v[192:195], v[96:99]
	v_mfma_f32_16x16x32_bf16 v[84:87], v[168:171], v[222:225], v[84:87]
	v_mfma_f32_16x16x32_bf16 v[80:83], v[176:179], v[222:225], v[80:83]
	v_mfma_f32_16x16x32_bf16 v[68:71], v[168:171], v[234:237], v[68:71]
	v_mfma_f32_16x16x32_bf16 v[64:67], v[176:179], v[234:237], v[64:67]
	v_mfma_f32_16x16x32_bf16 v[116:119], v[172:175], v[188:191], v[116:119]
	v_mfma_f32_16x16x32_bf16 v[112:115], v[180:183], v[188:191], v[112:115]
	v_mfma_f32_16x16x32_bf16 v[100:103], v[172:175], v[196:199], v[100:103]
	v_mfma_f32_16x16x32_bf16 v[96:99], v[180:183], v[196:199], v[96:99]
	v_mfma_f32_16x16x32_bf16 v[84:87], v[172:175], v[230:233], v[84:87]
	v_mfma_f32_16x16x32_bf16 v[80:83], v[180:183], v[230:233], v[80:83]
	v_mfma_f32_16x16x32_bf16 v[68:71], v[172:175], v[238:241], v[68:71]
	v_mfma_f32_16x16x32_bf16 v[64:67], v[180:183], v[238:241], v[64:67]
	s_setprio 0
	s_barrier
	s_add_i32 s20, s26, s66
	s_mov_b32 m0, s20
	ds_read_b128 v[184:187], v221 offset:16384
	ds_read_b128 v[188:191], v221 offset:17408
	ds_read_b128 v[192:195], v221 offset:18432
	ds_read_b128 v[196:199], v221 offset:19456
	ds_read_b128 v[222:225], v221 offset:20480
	ds_read_b128 v[230:233], v221 offset:21504
	ds_read_b128 v[234:237], v221 offset:22528
	ds_read_b128 v[238:241], v221 offset:23552
	global_load_lds_dwordx4 v158, s[30:31]
	s_add_i32 m0, s20, 0x2000
	s_add_u32 s20, s30, 0x40000
	s_addc_u32 s21, s31, 0
	s_add_i32 s26, s27, s66
	global_load_lds_dwordx4 v162, s[30:31]
	s_mov_b32 m0, s26
	s_nop 0
	global_load_lds_dwordx4 v158, s[20:21]
	s_add_i32 m0, s26, 0x2000
	s_nop 0
	global_load_lds_dwordx4 v162, s[20:21]
	s_mov_b32 m0, s76
	s_nop 0
	global_load_lds_dwordx4 v144, s[64:65]
	s_mov_b32 m0, s77
	s_nop 0
	global_load_lds_dwordx4 v160, s[64:65]
	s_waitcnt vmcnt(8)
	s_waitcnt lgkmcnt(0)
	s_barrier
; #define PG8_STAGE(bufoff, gbase, voff) do { _Pragma("unroll") for (int _i = 0; _i < 2; ++_i) \
;         __builtin_amdgcn_global_load_lds((const unsigned*)((const char*)(gbase) + (voff)[_i]), (LAS unsigned*)(lds + (bufoff) + ldsw + _i * 8192), 16, 0, 0); } while (0)
; #define PG8_LDA(dst, b, h) do { _Pragma("unroll") for (int m = 0; m < 4; ++m) _Pragma("unroll") for (int k = 0; k < 2; ++k) dst[m][k] = *(const LAS bf16x8*)(lds + PG8_SA(b, h) + aoff + m * 2048 + k * 1024); } while (0)
; #define PG8_LDB(dst, b, h) do { _Pragma("unroll") for (int n = 0; n < 2; ++n) _Pragma("unroll") for (int k = 0; k < 2; ++k) dst[n][k] = *(const LAS bf16x8*)(lds + PG8_SB(b, h) + boff + n * 2048 + k * 1024); } while (0)
; #define PG8_MMA(ai, bj, At, Bt) do { __builtin_amdgcn_s_setprio(1); _Pragma("unroll") for (int m = 0; m < 4; ++m) _Pragma("unroll") for (int n = 0; n < 2; ++n) _Pragma("unroll") for (int k = 0; k < 2; ++k) \
;         acc[ai][bj][m][n] = __builtin_amdgcn_mfma_f32_16x16x32_bf16(Bt[n][k], At[m][k], acc[ai][bj][m][n], 0, 0, 0); __builtin_amdgcn_s_setprio(0); } while (0)
; #define PG8_WAIT_V(n) asm volatile("s_waitcnt vmcnt(" #n ")" ::: "memory")
; #define PG8_WAIT_L(n) asm volatile("s_waitcnt lgkmcnt(" #n ")" ::: "memory")
; #define PG8_BAR __builtin_amdgcn_s_barrier()
; #define PG8_SCHED __builtin_amdgcn_sched_barrier(0)
; template <class Epi>
; DI void gemm_phase(LAS unsigned char* lds, const Gemm g, const StaticOrder S, const Epi E) {
;     ...
;             PG8_WAIT_V(8); PG8_WAIT_L(0); PG8_BAR; PG8_MMA(1, 0, At, B0); PG8_MMA(1, 1, At, B1); PG8_BAR; PG8_SCHED;
;             PG8_LDB(B0, 1, 0); PG8_LDB(B1, 1, 1); PG8_SCHED; PG8_LDA(At, 1, 0); PG8_STAGE(PG8_SA(0, 1), a2 + hstepA, voffA);
;             PG8_WAIT_V(8); PG8_WAIT_L(0); PG8_BAR; PG8_MMA(0, 0, At, B0); PG8_MMA(0, 1, At, B1); PG8_BAR; PG8_SCHED;
	s_setprio 1
	s_waitcnt lgkmcnt(0)
	v_mfma_f32_16x16x32_bf16 v[60:63], v[128:131], v[184:187], v[60:63]
	v_mfma_f32_16x16x32_bf16 v[56:59], v[136:139], v[184:187], v[56:59]
	v_mfma_f32_16x16x32_bf16 v[44:47], v[128:131], v[192:195], v[44:47]
	v_mfma_f32_16x16x32_bf16 v[40:43], v[136:139], v[192:195], v[40:43]
	v_mfma_f32_16x16x32_bf16 v[28:31], v[128:131], v[222:225], v[28:31]
	v_mfma_f32_16x16x32_bf16 v[24:27], v[136:139], v[222:225], v[24:27]
	v_mfma_f32_16x16x32_bf16 v[12:15], v[128:131], v[234:237], v[12:15]
	v_mfma_f32_16x16x32_bf16 v[8:11], v[136:139], v[234:237], v[8:11]
	v_mfma_f32_16x16x32_bf16 v[60:63], v[132:135], v[188:191], v[60:63]
	v_mfma_f32_16x16x32_bf16 v[56:59], v[140:143], v[188:191], v[56:59]
	v_mfma_f32_16x16x32_bf16 v[44:47], v[132:135], v[196:199], v[44:47]
	v_mfma_f32_16x16x32_bf16 v[40:43], v[140:143], v[196:199], v[40:43]
	v_mfma_f32_16x16x32_bf16 v[28:31], v[132:135], v[230:233], v[28:31]
	v_mfma_f32_16x16x32_bf16 v[24:27], v[140:143], v[230:233], v[24:27]
	v_mfma_f32_16x16x32_bf16 v[12:15], v[132:135], v[238:241], v[12:15]
	v_mfma_f32_16x16x32_bf16 v[8:11], v[140:143], v[238:241], v[8:11]
	s_setprio 0
	s_setprio 1
	v_mfma_f32_16x16x32_bf16 v[52:55], v[168:171], v[184:187], v[52:55]
	v_mfma_f32_16x16x32_bf16 v[48:51], v[176:179], v[184:187], v[48:51]
	v_mfma_f32_16x16x32_bf16 v[36:39], v[168:171], v[192:195], v[36:39]
	v_mfma_f32_16x16x32_bf16 v[32:35], v[176:179], v[192:195], v[32:35]
	v_mfma_f32_16x16x32_bf16 v[20:23], v[168:171], v[222:225], v[20:23]
	v_mfma_f32_16x16x32_bf16 v[16:19], v[176:179], v[222:225], v[16:19]
	v_mfma_f32_16x16x32_bf16 v[4:7], v[168:171], v[234:237], v[4:7]
	v_mfma_f32_16x16x32_bf16 v[0:3], v[176:179], v[234:237], v[0:3]
	v_mfma_f32_16x16x32_bf16 v[52:55], v[172:175], v[188:191], v[52:55]
	v_mfma_f32_16x16x32_bf16 v[48:51], v[180:183], v[188:191], v[48:51]
	v_mfma_f32_16x16x32_bf16 v[36:39], v[172:175], v[196:199], v[36:39]
	v_mfma_f32_16x16x32_bf16 v[32:35], v[180:183], v[196:199], v[32:35]
	v_mfma_f32_16x16x32_bf16 v[20:23], v[172:175], v[230:233], v[20:23]
	v_mfma_f32_16x16x32_bf16 v[16:19], v[180:183], v[230:233], v[16:19]
	v_mfma_f32_16x16x32_bf16 v[4:7], v[172:175], v[238:241], v[4:7]
	v_mfma_f32_16x16x32_bf16 v[0:3], v[180:183], v[238:241], v[0:3]
	s_setprio 0
	s_barrier
	s_add_i32 s26, 0, 0x1c000
	v_add_u32_e32 v140, s74, v220
	v_add_u32_e32 v146, s26, v220
	ds_read_b128 v[128:131], v140
	ds_read_b128 v[132:135], v140 offset:1024
	ds_read_b128 v[136:139], v140 offset:2048
	ds_read_b128 v[140:143], v140 offset:3072
	ds_read_b128 v[168:171], v146
	ds_read_b128 v[172:175], v146 offset:1024
	ds_read_b128 v[176:179], v146 offset:2048
	ds_read_b128 v[180:183], v146 offset:3072
	s_add_u32 s20, s64, 0x40000
	s_addc_u32 s21, s65, 0
	s_mov_b32 m0, s78
	ds_read_b128 v[184:187], v221 offset:32768
	ds_read_b128 v[188:191], v221 offset:33792
	ds_read_b128 v[192:195], v221 offset:34816
	ds_read_b128 v[196:199], v221 offset:35840
	ds_read_b128 v[222:225], v221 offset:36864
	ds_read_b128 v[230:233], v221 offset:37888
	ds_read_b128 v[234:237], v221 offset:38912
	ds_read_b128 v[238:241], v221 offset:39936
	global_load_lds_dwordx4 v144, s[20:21]
	s_mov_b32 m0, s79
	s_nop 0
	global_load_lds_dwordx4 v160, s[20:21]
	s_waitcnt vmcnt(8)
	s_waitcnt lgkmcnt(0)
	s_barrier
	s_setprio 1
	s_waitcnt lgkmcnt(0)
	v_mfma_f32_16x16x32_bf16 v[124:127], v[128:131], v[184:187], v[124:127]
	v_mfma_f32_16x16x32_bf16 v[120:123], v[136:139], v[184:187], v[120:123]
	v_mfma_f32_16x16x32_bf16 v[108:111], v[128:131], v[192:195], v[108:111]
	v_mfma_f32_16x16x32_bf16 v[104:107], v[136:139], v[192:195], v[104:107]
	v_mfma_f32_16x16x32_bf16 v[92:95], v[128:131], v[222:225], v[92:95]
	v_mfma_f32_16x16x32_bf16 v[88:91], v[136:139], v[222:225], v[88:91]
	v_mfma_f32_16x16x32_bf16 v[76:79], v[128:131], v[234:237], v[76:79]
	v_mfma_f32_16x16x32_bf16 v[72:75], v[136:139], v[234:237], v[72:75]
	v_mfma_f32_16x16x32_bf16 v[124:127], v[132:135], v[188:191], v[124:127]
	v_mfma_f32_16x16x32_bf16 v[120:123], v[140:143], v[188:191], v[120:123]
	v_mfma_f32_16x16x32_bf16 v[108:111], v[132:135], v[196:199], v[108:111]
	v_mfma_f32_16x16x32_bf16 v[104:107], v[140:143], v[196:199], v[104:107]
	v_mfma_f32_16x16x32_bf16 v[92:95], v[132:135], v[230:233], v[92:95]
	v_mfma_f32_16x16x32_bf16 v[88:91], v[140:143], v[230:233], v[88:91]
	v_mfma_f32_16x16x32_bf16 v[76:79], v[132:135], v[238:241], v[76:79]
	v_mfma_f32_16x16x32_bf16 v[72:75], v[140:143], v[238:241], v[72:75]
	s_setprio 0
	s_setprio 1
	v_mfma_f32_16x16x32_bf16 v[116:119], v[168:171], v[184:187], v[116:119]
	v_mfma_f32_16x16x32_bf16 v[112:115], v[176:179], v[184:187], v[112:115]
	v_mfma_f32_16x16x32_bf16 v[100:103], v[168:171], v[192:195], v[100:103]
	v_mfma_f32_16x16x32_bf16 v[96:99], v[176:179], v[192:195], v[96:99]
	v_mfma_f32_16x16x32_bf16 v[84:87], v[168:171], v[222:225], v[84:87]
	v_mfma_f32_16x16x32_bf16 v[80:83], v[176:179], v[222:225], v[80:83]
	v_mfma_f32_16x16x32_bf16 v[68:71], v[168:171], v[234:237], v[68:71]
	v_mfma_f32_16x16x32_bf16 v[64:67], v[176:179], v[234:237], v[64:67]
	v_mfma_f32_16x16x32_bf16 v[116:119], v[172:175], v[188:191], v[116:119]
	v_mfma_f32_16x16x32_bf16 v[112:115], v[180:183], v[188:191], v[112:115]
	v_mfma_f32_16x16x32_bf16 v[100:103], v[172:175], v[196:199], v[100:103]
	v_mfma_f32_16x16x32_bf16 v[96:99], v[180:183], v[196:199], v[96:99]
	v_mfma_f32_16x16x32_bf16 v[84:87], v[172:175], v[230:233], v[84:87]
	v_mfma_f32_16x16x32_bf16 v[80:83], v[180:183], v[230:233], v[80:83]
	v_mfma_f32_16x16x32_bf16 v[68:71], v[172:175], v[238:241], v[68:71]
	v_mfma_f32_16x16x32_bf16 v[64:67], v[180:183], v[238:241], v[64:67]
	s_setprio 0
	s_barrier
; #define PG8_STAGE(bufoff, gbase, voff) do { _Pragma("unroll") for (int _i = 0; _i < 2; ++_i) \
;         __builtin_amdgcn_global_load_lds((const unsigned*)((const char*)(gbase) + (voff)[_i]), (LAS unsigned*)(lds + (bufoff) + ldsw + _i * 8192), 16, 0, 0); } while (0)
; #define PG8_LDA(dst, b, h) do { _Pragma("unroll") for (int m = 0; m < 4; ++m) _Pragma("unroll") for (int k = 0; k < 2; ++k) dst[m][k] = *(const LAS bf16x8*)(lds + PG8_SA(b, h) + aoff + m * 2048 + k * 1024); } while (0)
; #define PG8_MMA(ai, bj, At, Bt) do { __builtin_amdgcn_s_setprio(1); _Pragma("unroll") for (int m = 0; m < 4; ++m) _Pragma("unroll") for (int n = 0; n < 2; ++n) _Pragma("unroll") for (int k = 0; k < 2; ++k) \
;         acc[ai][bj][m][n] = __builtin_amdgcn_mfma_f32_16x16x32_bf16(Bt[n][k], At[m][k], acc[ai][bj][m][n], 0, 0, 0); __builtin_amdgcn_s_setprio(0); } while (0)
; #define PG8_WAIT_V(n) asm volatile("s_waitcnt vmcnt(" #n ")" ::: "memory")
; #define PG8_WAIT_L(n) asm volatile("s_waitcnt lgkmcnt(" #n ")" ::: "memory")
; #define PG8_BAR __builtin_amdgcn_s_barrier()
; #define PG8_SCHED __builtin_amdgcn_sched_barrier(0)
; template <class Epi>
; DI void gemm_phase(LAS unsigned char* lds, const Gemm g, const StaticOrder S, const Epi E) {
;     ...
;             PG8_LDA(At, 1, 1); PG8_STAGE(PG8_SB(1, 0), b3, voffB); PG8_STAGE(PG8_SB(1, 1), b3 + hstepB, voffB); PG8_STAGE(PG8_SA(1, 0), a3, voffA);
;             PG8_WAIT_V(8); PG8_WAIT_L(0); PG8_BAR; PG8_MMA(1, 0, At, B0); PG8_MMA(1, 1, At, B1); PG8_BAR; PG8_SCHED;
;         }
	s_add_i32 s20, s74, s66
	s_mov_b32 m0, s20
	ds_read_b128 v[184:187], v221 offset:49152
	ds_read_b128 v[188:191], v221 offset:50176
	ds_read_b128 v[192:195], v221 offset:51200
	ds_read_b128 v[196:199], v221 offset:52224
	ds_read_b128 v[222:225], v221 offset:53248
	ds_read_b128 v[230:233], v221 offset:54272
	ds_read_b128 v[234:237], v221 offset:55296
	ds_read_b128 v[238:241], v221 offset:56320
	global_load_lds_dwordx4 v158, s[98:99]
	s_add_i32 m0, s20, 0x2000
	s_add_u32 s20, s30, 0x40080
	s_addc_u32 s21, s31, 0
	s_add_i32 s26, s26, s66
	global_load_lds_dwordx4 v162, s[98:99]
	s_mov_b32 m0, s26
	s_nop 0
	global_load_lds_dwordx4 v158, s[20:21]
	s_add_i32 m0, s26, 0x2000
	s_nop 0
	global_load_lds_dwordx4 v162, s[20:21]
	s_mov_b32 m0, s88
	s_nop 0
	global_load_lds_dwordx4 v144, s[100:101]
	s_mov_b32 m0, s22
	s_nop 0
	global_load_lds_dwordx4 v160, s[100:101]
	s_waitcnt vmcnt(8)
	s_waitcnt lgkmcnt(0)
	s_barrier
	s_setprio 1
	s_waitcnt lgkmcnt(0)
	v_mfma_f32_16x16x32_bf16 v[60:63], v[128:131], v[184:187], v[60:63]
	v_mfma_f32_16x16x32_bf16 v[56:59], v[136:139], v[184:187], v[56:59]
	v_mfma_f32_16x16x32_bf16 v[44:47], v[128:131], v[192:195], v[44:47]
	v_mfma_f32_16x16x32_bf16 v[40:43], v[136:139], v[192:195], v[40:43]
	v_mfma_f32_16x16x32_bf16 v[28:31], v[128:131], v[222:225], v[28:31]
	v_mfma_f32_16x16x32_bf16 v[24:27], v[136:139], v[222:225], v[24:27]
	v_mfma_f32_16x16x32_bf16 v[12:15], v[128:131], v[234:237], v[12:15]
	v_mfma_f32_16x16x32_bf16 v[8:11], v[136:139], v[234:237], v[8:11]
	v_mfma_f32_16x16x32_bf16 v[60:63], v[132:135], v[188:191], v[60:63]
	v_mfma_f32_16x16x32_bf16 v[56:59], v[140:143], v[188:191], v[56:59]
	v_mfma_f32_16x16x32_bf16 v[44:47], v[132:135], v[196:199], v[44:47]
	v_mfma_f32_16x16x32_bf16 v[40:43], v[140:143], v[196:199], v[40:43]
	v_mfma_f32_16x16x32_bf16 v[28:31], v[132:135], v[230:233], v[28:31]
	v_mfma_f32_16x16x32_bf16 v[24:27], v[140:143], v[230:233], v[24:27]
	v_mfma_f32_16x16x32_bf16 v[12:15], v[132:135], v[238:241], v[12:15]
	v_mfma_f32_16x16x32_bf16 v[8:11], v[140:143], v[238:241], v[8:11]
	s_setprio 0
	s_setprio 1
	v_mfma_f32_16x16x32_bf16 v[52:55], v[168:171], v[184:187], v[52:55]
	v_mfma_f32_16x16x32_bf16 v[48:51], v[176:179], v[184:187], v[48:51]
	v_mfma_f32_16x16x32_bf16 v[36:39], v[168:171], v[192:195], v[36:39]
	v_mfma_f32_16x16x32_bf16 v[32:35], v[176:179], v[192:195], v[32:35]
	v_mfma_f32_16x16x32_bf16 v[20:23], v[168:171], v[222:225], v[20:23]
	v_mfma_f32_16x16x32_bf16 v[16:19], v[176:179], v[222:225], v[16:19]
	v_mfma_f32_16x16x32_bf16 v[4:7], v[168:171], v[234:237], v[4:7]
	v_mfma_f32_16x16x32_bf16 v[0:3], v[176:179], v[234:237], v[0:3]
	v_mfma_f32_16x16x32_bf16 v[52:55], v[172:175], v[188:191], v[52:55]
	v_mfma_f32_16x16x32_bf16 v[48:51], v[180:183], v[188:191], v[48:51]
	v_mfma_f32_16x16x32_bf16 v[36:39], v[172:175], v[196:199], v[36:39]
	v_mfma_f32_16x16x32_bf16 v[32:35], v[180:183], v[196:199], v[32:35]
	v_mfma_f32_16x16x32_bf16 v[20:23], v[172:175], v[230:233], v[20:23]
	v_mfma_f32_16x16x32_bf16 v[16:19], v[180:183], v[230:233], v[16:19]
	v_mfma_f32_16x16x32_bf16 v[4:7], v[172:175], v[238:241], v[4:7]
	v_mfma_f32_16x16x32_bf16 v[0:3], v[180:183], v[238:241], v[0:3]
	s_setprio 0
	s_barrier
	s_add_i32 s57, s57, 2
	s_add_u32 s42, s42, 0x100
	s_addc_u32 s43, s43, 0
	s_add_u32 s3, s3, 0x100
	s_addc_u32 s55, s55, 0
	s_cmp_gt_u32 s57, 13
	s_cbranch_scc0 .LBB0_335
	s_and_b64 vcc, exec, s[52:53]
	s_cbranch_vccz .LBB0_338
	s_barrier
